# write-through (sc1) dwordx4 stores in in-proj epilogues and mixers (phases followed by global seams)
# speedup vs baseline: 1.0325x; 1.0325x over previous
.LBB0_203:
	ds_bpermute_b32 v32, v194, v210
	s_lshl_b64 s[2:3], s[2:3], 1
	s_add_u32 s8, s79, s2
	s_addc_u32 s16, s80, s3
	v_lshlrev_b32_e32 v158, 1, v146
	s_waitcnt lgkmcnt(0)
	v_add_f32_e32 v32, v210, v32
	v_div_scale_f32 v33, s[2:3], v32, v32, 1.0
	v_rcp_f32_e32 v34, v33
	s_lshl_b32 s2, s24, 1
	s_add_u32 s2, s8, s2
	s_movk_i32 s8, 0x50
	v_fma_f32 v35, -v33, v34, 1.0
	v_fmac_f32_e32 v34, v35, v34
	v_div_scale_f32 v35, vcc, 1.0, v32, 1.0
	v_mul_f32_e32 v36, v35, v34
	v_fma_f32 v37, -v33, v36, v35
	v_fmac_f32_e32 v36, v37, v34
	v_fma_f32 v33, -v33, v36, v35
	v_div_fmas_f32 v33, v33, v34, v36
	v_div_fixup_f32 v32, v33, v32, 1.0
	v_ashrrev_i32_e32 v33, 2, v149
	v_and_b32_e32 v33, -8, v33
	v_add_u32_e32 v33, v190, v33
	v_pk_mul_f32 v[0:1], v[0:1], v[32:33] op_sel_hi:[1,0]
	v_pk_mul_f32 v[2:3], v[2:3], v[32:33] op_sel_hi:[1,0]
	v_pk_mul_f32 v[16:17], v[16:17], v[32:33] op_sel_hi:[1,0]
	v_pk_mul_f32 v[18:19], v[18:19], v[32:33] op_sel_hi:[1,0]
	v_cvt_pk_bf16_f32 v0, v0, v1
	v_cvt_pk_bf16_f32 v1, v2, v3
	v_lshlrev_b32_e32 v2, 4, v147
	v_cvt_pk_bf16_f32 v16, v16, v17
	v_cvt_pk_bf16_f32 v17, v18, v19
	v_and_b32_e32 v18, 0x70, v2
	v_add_u32_e32 v2, v33, v18
	ds_write_b64 v2, v[16:17]
	v_xad_u32 v2, v18, 64, v33
	ds_write_b64 v2, v[0:1]
	v_pk_mul_f32 v[0:1], v[20:21], v[32:33] op_sel_hi:[1,0]
	v_pk_mul_f32 v[2:3], v[22:23], v[32:33] op_sel_hi:[1,0]
	v_cvt_pk_bf16_f32 v0, v0, v1
	v_cvt_pk_bf16_f32 v1, v2, v3
	v_pk_mul_f32 v[2:3], v[4:5], v[32:33] op_sel_hi:[1,0]
	v_pk_mul_f32 v[4:5], v[6:7], v[32:33] op_sel_hi:[1,0]
	v_cvt_pk_bf16_f32 v2, v2, v3
	v_cvt_pk_bf16_f32 v3, v4, v5
	v_xad_u32 v4, v18, 16, v33
	ds_write_b64 v4, v[0:1]
	v_xad_u32 v0, v18, s8, v33
	ds_write_b64 v0, v[2:3]
	v_pk_mul_f32 v[0:1], v[24:25], v[32:33] op_sel_hi:[1,0]
	v_pk_mul_f32 v[2:3], v[26:27], v[32:33] op_sel_hi:[1,0]
	v_cvt_pk_bf16_f32 v0, v0, v1
	v_cvt_pk_bf16_f32 v1, v2, v3
	v_pk_mul_f32 v[2:3], v[8:9], v[32:33] op_sel_hi:[1,0]
	v_pk_mul_f32 v[4:5], v[10:11], v[32:33] op_sel_hi:[1,0]
	v_cvt_pk_bf16_f32 v2, v2, v3
	v_cvt_pk_bf16_f32 v3, v4, v5
	v_xad_u32 v4, v18, 32, v33
	s_movk_i32 s8, 0x60
	ds_write_b64 v4, v[0:1]
	v_xad_u32 v0, v18, s8, v33
	ds_write_b64 v0, v[2:3]
	v_pk_mul_f32 v[0:1], v[28:29], v[32:33] op_sel_hi:[1,0]
	v_pk_mul_f32 v[2:3], v[30:31], v[32:33] op_sel_hi:[1,0]
	v_cvt_pk_bf16_f32 v0, v0, v1
	v_cvt_pk_bf16_f32 v1, v2, v3
	v_pk_mul_f32 v[2:3], v[12:13], v[32:33] op_sel_hi:[1,0]
	v_pk_mul_f32 v[4:5], v[14:15], v[32:33] op_sel_hi:[1,0]
	v_cvt_pk_bf16_f32 v2, v2, v3
	v_cvt_pk_bf16_f32 v3, v4, v5
	v_xad_u32 v4, v18, 48, v33
	s_movk_i32 s8, 0x70
	ds_write_b64 v4, v[0:1]
	v_xad_u32 v0, v18, s8, v33
	ds_write_b64 v0, v[2:3]
	ds_read_b128 v[2:5], v153
	s_addc_u32 s3, s16, 0
	v_lshl_add_u64 v[6:7], s[2:3], 0, v[158:159]
	s_mov_b64 s[2:3], 0x600
	v_lshl_add_u64 v[0:1], v[6:7], 0, s[2:3]
	v_lshl_add_u64 v[6:7], v[6:7], 0, v[154:155]
	s_mov_b64 s[2:3], 0
	s_waitcnt lgkmcnt(0)
	global_store_dwordx4 v[6:7], v[2:5], off offset:1536 sc1

.LBB0_213:
	s_lshl_b32 s24, s24, 7
	s_ashr_i32 s25, s24, 31
	s_mul_i32 s34, s6, 0x600
	s_mul_hi_i32 s8, s6, 0x600
	s_add_u32 s34, s36, s34
	s_addc_u32 s8, s37, s8
	s_lshl_b64 s[6:7], s[6:7], 11
	s_add_u32 s35, s79, s6
	s_addc_u32 s39, s80, s7
	s_lshl_b64 s[6:7], s[24:25], 2
	s_add_u32 s42, s2, s6
	s_addc_u32 s43, s3, s7
	s_add_u32 s6, s40, s47
	s_addc_u32 s7, s41, 0
	s_lshl_b64 s[2:3], s[16:17], 2
	s_add_u32 s24, s6, s2
	s_addc_u32 s25, s7, s3
	s_lshl_b64 s[6:7], s[16:17], 1
	s_add_u32 s2, s34, s6
	s_addc_u32 s3, s8, s7
	s_add_u32 s6, s35, s6
	s_addc_u32 s7, s39, s7
	s_lshl_b32 s8, s38, 2
	s_add_u32 s16, s42, s8
	s_waitcnt vmcnt(6)
	v_lshlrev_b32_e32 v64, 2, v193
	s_addc_u32 s17, s43, 0
	v_ashrrev_i32_e32 v65, 31, v64
	v_lshl_add_u64 v[64:65], v[64:65], 2, s[16:17]
	s_waitcnt vmcnt(3)
	v_lshlrev_b32_e32 v81, 2, v192
	global_load_dwordx4 v[76:79], v[64:65], off
	global_load_dwordx4 v[72:75], v[64:65], off offset:32
	global_load_dwordx4 v[68:71], v[64:65], off offset:64
	s_nop 0
	global_load_dwordx4 v[64:67], v[64:65], off offset:96
	v_lshlrev_b32_e32 v80, 11, v193
	global_load_dword v82, v81, s[24:25]
	v_add3_u32 v80, s33, v80, v81
	v_add_u32_e32 v144, s38, v147
	s_waitcnt vmcnt(0)
	v_fma_f32 v48, v48, v82, v76
	v_fma_f32 v49, v49, v82, v77
	v_fma_f32 v50, v50, v82, v78
	v_fma_f32 v51, v51, v82, v79
	v_fma_f32 v52, v52, v82, v72
	v_fma_f32 v53, v53, v82, v73
	v_fma_f32 v54, v54, v82, v74
	v_fma_f32 v55, v55, v82, v75
	v_fma_f32 v56, v56, v82, v68
	v_fma_f32 v57, v57, v82, v69
	v_fma_f32 v58, v58, v82, v70
	v_fma_f32 v59, v59, v82, v71
	v_fma_f32 v60, v60, v82, v64
	v_fma_f32 v61, v61, v82, v65
	v_fma_f32 v62, v62, v82, v66
	v_fma_f32 v63, v63, v82, v67
	global_load_dword v82, v81, s[24:25] offset:128
	s_waitcnt vmcnt(0)
	v_fma_f32 v32, v32, v82, v76
	ds_write2_b32 v80, v48, v32 offset1:32
	v_fma_f32 v32, v33, v82, v77
	ds_write2_b32 v80, v49, v32 offset0:128 offset1:160
	v_fma_f32 v32, v34, v82, v78
	v_add_u32_e32 v33, 0x400, v80
	ds_write2_b32 v33, v50, v32 offset1:32
	v_fma_f32 v32, v35, v82, v79
	ds_write2_b32 v33, v51, v32 offset0:128 offset1:160
	v_fma_f32 v32, v36, v82, v72
	v_add_u32_e32 v34, 0x1000, v80
	ds_write2_b32 v34, v52, v32 offset1:32
	v_fma_f32 v32, v37, v82, v73
	ds_write2_b32 v34, v53, v32 offset0:128 offset1:160
	v_fma_f32 v32, v38, v82, v74
	v_add_u32_e32 v35, 0x1400, v80
	ds_write2_b32 v35, v54, v32 offset1:32
	v_fma_f32 v32, v39, v82, v75
	ds_write2_b32 v35, v55, v32 offset0:128 offset1:160
	v_fma_f32 v32, v40, v82, v68
	v_add_u32_e32 v36, 0x2000, v80
	ds_write2_b32 v36, v56, v32 offset1:32
	v_fma_f32 v32, v41, v82, v69
	ds_write2_b32 v36, v57, v32 offset0:128 offset1:160
	v_fma_f32 v32, v42, v82, v70
	v_add_u32_e32 v37, 0x2400, v80
	ds_write2_b32 v37, v58, v32 offset1:32
	v_fma_f32 v32, v43, v82, v71
	ds_write2_b32 v37, v59, v32 offset0:128 offset1:160
	v_fma_f32 v32, v44, v82, v64
	v_add_u32_e32 v38, 0x3000, v80
	ds_write2_b32 v38, v60, v32 offset1:32
	v_fma_f32 v32, v45, v82, v65
	ds_write2_b32 v38, v61, v32 offset0:128 offset1:160
	v_fma_f32 v32, v46, v82, v66
	v_add_u32_e32 v39, 0x3400, v80
	ds_write2_b32 v39, v62, v32 offset1:32
	v_fma_f32 v32, v47, v82, v67
	ds_write2_b32 v39, v63, v32 offset0:128 offset1:160
	global_load_dword v32, v81, s[24:25] offset:256
	s_waitcnt vmcnt(0)
	v_fma_f32 v16, v16, v32, v76
	v_fma_f32 v17, v17, v32, v77
	v_fma_f32 v18, v18, v32, v78
	v_fma_f32 v19, v19, v32, v79
	v_fma_f32 v20, v20, v32, v72
	v_fma_f32 v21, v21, v32, v73
	v_fma_f32 v22, v22, v32, v74
	v_fma_f32 v23, v23, v32, v75
	v_fma_f32 v24, v24, v32, v68
	v_fma_f32 v25, v25, v32, v69
	v_fma_f32 v26, v26, v32, v70
	v_fma_f32 v27, v27, v32, v71
	v_fma_f32 v28, v28, v32, v64
	v_fma_f32 v29, v29, v32, v65
	v_fma_f32 v30, v30, v32, v66
	v_fma_f32 v31, v31, v32, v67
	global_load_dword v32, v81, s[24:25] offset:384
	s_waitcnt vmcnt(0)
	v_fma_f32 v0, v0, v32, v76
	ds_write2_b32 v80, v16, v0 offset0:64 offset1:96
	v_fma_f32 v0, v1, v32, v77
	ds_write2_b32 v80, v17, v0 offset0:192 offset1:224
	v_fma_f32 v0, v2, v32, v78
	ds_write2_b32 v33, v18, v0 offset0:64 offset1:96
	v_fma_f32 v0, v4, v32, v72
	ds_write2_b32 v34, v20, v0 offset0:64 offset1:96
	v_fma_f32 v0, v5, v32, v73
	ds_write2_b32 v34, v21, v0 offset0:192 offset1:224
	v_fma_f32 v0, v6, v32, v74
	ds_write2_b32 v35, v22, v0 offset0:64 offset1:96
	v_fma_f32 v0, v8, v32, v68
	ds_write2_b32 v36, v24, v0 offset0:64 offset1:96
	v_fma_f32 v0, v9, v32, v69
	ds_write2_b32 v36, v25, v0 offset0:192 offset1:224
	v_fma_f32 v0, v10, v32, v70
	ds_write2_b32 v37, v26, v0 offset0:64 offset1:96
	v_fma_f32 v0, v12, v32, v64
	ds_write2_b32 v38, v28, v0 offset0:64 offset1:96
	v_fma_f32 v0, v13, v32, v65
	ds_write2_b32 v38, v29, v0 offset0:192 offset1:224
	v_fma_f32 v0, v14, v32, v66
	ds_write2_b32 v39, v30, v0 offset0:64 offset1:96
	v_lshl_add_u64 v[0:1], s[2:3], 0, v[158:159]
	v_fmac_f32_e32 v79, v3, v32
	v_mad_i64_i32 v[2:3], s[2:3], v148, s69, v[0:1]
	v_fmac_f32_e32 v71, v11, v32
	global_load_dwordx4 v[8:11], v[2:3], off
	v_fmac_f32_e32 v75, v7, v32
	v_fmac_f32_e32 v67, v15, v32
	v_lshl_add_u32 v6, v149, 5, s33
	ds_write2_b32 v33, v19, v79 offset0:192 offset1:224
	ds_write2_b32 v35, v23, v75 offset0:192 offset1:224
	ds_write2_b32 v37, v27, v71 offset0:192 offset1:224
	ds_write2_b32 v39, v31, v67 offset0:192 offset1:224
	v_lshl_add_u32 v2, v213, 9, v6
	ds_read_b128 v[12:15], v2
	ds_read_b128 v[16:19], v2 offset:16
	v_ashrrev_i32_e32 v149, 31, v148
	v_lshl_add_u64 v[4:5], s[6:7], 0, v[158:159]
	v_lshl_add_u32 v7, v205, 9, v6
	s_waitcnt vmcnt(0)
	v_lshlrev_b32_e32 v2, 16, v8
	v_and_b32_e32 v3, 0xffff0000, v8
	s_waitcnt lgkmcnt(1)
	v_pk_mul_f32 v[2:3], v[12:13], v[2:3]
	s_nop 0
	v_cvt_pk_bf16_f32 v8, v2, v3
	v_lshlrev_b32_e32 v2, 16, v9
	v_and_b32_e32 v3, 0xffff0000, v9
	v_pk_mul_f32 v[2:3], v[14:15], v[2:3]
	s_nop 0
	v_cvt_pk_bf16_f32 v9, v2, v3
	v_lshlrev_b32_e32 v2, 16, v10
	v_and_b32_e32 v3, 0xffff0000, v10
	s_waitcnt lgkmcnt(0)
	v_pk_mul_f32 v[2:3], v[16:17], v[2:3]
	s_nop 0
	v_cvt_pk_bf16_f32 v10, v2, v3
	v_lshlrev_b32_e32 v2, 16, v11
	v_and_b32_e32 v3, 0xffff0000, v11
	v_pk_mul_f32 v[2:3], v[18:19], v[2:3]
	s_nop 0
	v_cvt_pk_bf16_f32 v11, v2, v3
	v_lshlrev_b64 v[2:3], 11, v[148:149]
	v_lshl_add_u64 v[2:3], v[4:5], 0, v[2:3]
	global_store_dwordx4 v[2:3], v[8:11], off sc1
	v_add_u32_e32 v2, s38, v205
	v_ashrrev_i32_e32 v3, 31, v2
	v_mad_i64_i32 v[8:9], s[2:3], v2, s69, v[0:1]
	global_load_dwordx4 v[8:11], v[8:9], off
	ds_read_b128 v[12:15], v7
	ds_read_b128 v[16:19], v7 offset:16
	v_lshlrev_b64 v[2:3], 11, v[2:3]
	v_lshl_add_u64 v[2:3], v[4:5], 0, v[2:3]
	v_lshl_add_u32 v7, v202, 9, v6
	s_waitcnt vmcnt(0)
	v_lshlrev_b32_e32 v20, 16, v8
	v_and_b32_e32 v21, 0xffff0000, v8
	s_waitcnt lgkmcnt(1)
	v_pk_mul_f32 v[12:13], v[12:13], v[20:21]
	s_nop 0
	v_cvt_pk_bf16_f32 v8, v12, v13
	v_lshlrev_b32_e32 v12, 16, v9
	v_and_b32_e32 v13, 0xffff0000, v9
	v_pk_mul_f32 v[12:13], v[14:15], v[12:13]
	s_nop 0
	v_cvt_pk_bf16_f32 v9, v12, v13
	v_lshlrev_b32_e32 v12, 16, v10
	v_and_b32_e32 v13, 0xffff0000, v10
	s_waitcnt lgkmcnt(0)
	v_pk_mul_f32 v[12:13], v[16:17], v[12:13]
	s_nop 0
	v_cvt_pk_bf16_f32 v10, v12, v13
	v_lshlrev_b32_e32 v12, 16, v11
	v_and_b32_e32 v13, 0xffff0000, v11
	v_pk_mul_f32 v[12:13], v[18:19], v[12:13]
	s_nop 0
	v_cvt_pk_bf16_f32 v11, v12, v13
	global_store_dwordx4 v[2:3], v[8:11], off sc1
	v_add_u32_e32 v2, s38, v202
	v_ashrrev_i32_e32 v3, 31, v2
	v_mad_i64_i32 v[8:9], s[2:3], v2, s69, v[0:1]
	global_load_dwordx4 v[8:11], v[8:9], off
	ds_read_b128 v[12:15], v7
	ds_read_b128 v[16:19], v7 offset:16
	v_lshlrev_b64 v[2:3], 11, v[2:3]
	v_lshl_add_u64 v[2:3], v[4:5], 0, v[2:3]
	v_lshl_add_u32 v7, v201, 9, v6
	s_waitcnt vmcnt(0)
	v_lshlrev_b32_e32 v20, 16, v8
	v_and_b32_e32 v21, 0xffff0000, v8
	s_waitcnt lgkmcnt(1)
	v_pk_mul_f32 v[12:13], v[12:13], v[20:21]
	s_nop 0
	v_cvt_pk_bf16_f32 v8, v12, v13
	v_lshlrev_b32_e32 v12, 16, v9
	v_and_b32_e32 v13, 0xffff0000, v9
	v_pk_mul_f32 v[12:13], v[14:15], v[12:13]
	s_nop 0
	v_cvt_pk_bf16_f32 v9, v12, v13
	v_lshlrev_b32_e32 v12, 16, v10
	v_and_b32_e32 v13, 0xffff0000, v10
	s_waitcnt lgkmcnt(0)
	v_pk_mul_f32 v[12:13], v[16:17], v[12:13]
	s_nop 0
	v_cvt_pk_bf16_f32 v10, v12, v13
	v_lshlrev_b32_e32 v12, 16, v11
	v_and_b32_e32 v13, 0xffff0000, v11
	v_pk_mul_f32 v[12:13], v[18:19], v[12:13]
	s_nop 0
	v_cvt_pk_bf16_f32 v11, v12, v13
	global_store_dwordx4 v[2:3], v[8:11], off sc1
	v_add_u32_e32 v2, s38, v201
	v_ashrrev_i32_e32 v3, 31, v2
	v_mad_i64_i32 v[8:9], s[2:3], v2, s69, v[0:1]
	global_load_dwordx4 v[8:11], v[8:9], off
	ds_read_b128 v[12:15], v7
	ds_read_b128 v[16:19], v7 offset:16
	v_lshlrev_b64 v[2:3], 11, v[2:3]
	v_lshl_add_u64 v[2:3], v[4:5], 0, v[2:3]
	v_lshl_add_u32 v7, v200, 9, v6
	s_waitcnt vmcnt(0)
	v_lshlrev_b32_e32 v20, 16, v8
	v_and_b32_e32 v21, 0xffff0000, v8
	s_waitcnt lgkmcnt(1)
	v_pk_mul_f32 v[12:13], v[12:13], v[20:21]
	s_nop 0
	v_cvt_pk_bf16_f32 v8, v12, v13
	v_lshlrev_b32_e32 v12, 16, v9
	v_and_b32_e32 v13, 0xffff0000, v9
	v_pk_mul_f32 v[12:13], v[14:15], v[12:13]
	s_nop 0
	v_cvt_pk_bf16_f32 v9, v12, v13
	v_lshlrev_b32_e32 v12, 16, v10
	v_and_b32_e32 v13, 0xffff0000, v10
	s_waitcnt lgkmcnt(0)
	v_pk_mul_f32 v[12:13], v[16:17], v[12:13]
	s_nop 0
	v_cvt_pk_bf16_f32 v10, v12, v13
	v_lshlrev_b32_e32 v12, 16, v11
	v_and_b32_e32 v13, 0xffff0000, v11
	v_pk_mul_f32 v[12:13], v[18:19], v[12:13]
	s_nop 0
	v_cvt_pk_bf16_f32 v11, v12, v13
	global_store_dwordx4 v[2:3], v[8:11], off sc1
	v_add_u32_e32 v2, s38, v200
	v_ashrrev_i32_e32 v3, 31, v2
	v_mad_i64_i32 v[8:9], s[2:3], v2, s69, v[0:1]
	global_load_dwordx4 v[8:11], v[8:9], off
	ds_read_b128 v[12:15], v7
	ds_read_b128 v[16:19], v7 offset:16
	v_lshlrev_b64 v[2:3], 11, v[2:3]
	v_lshl_add_u64 v[2:3], v[4:5], 0, v[2:3]
	v_lshl_add_u32 v7, v199, 9, v6
	s_waitcnt vmcnt(0)
	v_lshlrev_b32_e32 v20, 16, v8
	v_and_b32_e32 v21, 0xffff0000, v8
	s_waitcnt lgkmcnt(1)
	v_pk_mul_f32 v[12:13], v[12:13], v[20:21]
	s_nop 0
	v_cvt_pk_bf16_f32 v8, v12, v13
	v_lshlrev_b32_e32 v12, 16, v9
	v_and_b32_e32 v13, 0xffff0000, v9
	v_pk_mul_f32 v[12:13], v[14:15], v[12:13]
	s_nop 0
	v_cvt_pk_bf16_f32 v9, v12, v13
	v_lshlrev_b32_e32 v12, 16, v10
	v_and_b32_e32 v13, 0xffff0000, v10
	s_waitcnt lgkmcnt(0)
	v_pk_mul_f32 v[12:13], v[16:17], v[12:13]
	s_nop 0
	v_cvt_pk_bf16_f32 v10, v12, v13
	v_lshlrev_b32_e32 v12, 16, v11
	v_and_b32_e32 v13, 0xffff0000, v11
	v_pk_mul_f32 v[12:13], v[18:19], v[12:13]
	s_nop 0
	v_cvt_pk_bf16_f32 v11, v12, v13
	global_store_dwordx4 v[2:3], v[8:11], off sc1
	v_add_u32_e32 v2, s38, v199
	v_ashrrev_i32_e32 v3, 31, v2
	v_mad_i64_i32 v[8:9], s[2:3], v2, s69, v[0:1]
	global_load_dwordx4 v[8:11], v[8:9], off
	ds_read_b128 v[12:15], v7
	ds_read_b128 v[16:19], v7 offset:16
	v_lshlrev_b64 v[2:3], 11, v[2:3]
	v_lshl_add_u64 v[2:3], v[4:5], 0, v[2:3]
	v_lshl_add_u32 v7, v145, 9, v6
	s_waitcnt vmcnt(0)
	v_lshlrev_b32_e32 v20, 16, v8
	v_and_b32_e32 v21, 0xffff0000, v8
	s_waitcnt lgkmcnt(1)
	v_pk_mul_f32 v[12:13], v[12:13], v[20:21]
	s_nop 0
	v_cvt_pk_bf16_f32 v8, v12, v13
	v_lshlrev_b32_e32 v12, 16, v9
	v_and_b32_e32 v13, 0xffff0000, v9
	v_pk_mul_f32 v[12:13], v[14:15], v[12:13]
	s_nop 0
	v_cvt_pk_bf16_f32 v9, v12, v13
	v_lshlrev_b32_e32 v12, 16, v10
	v_and_b32_e32 v13, 0xffff0000, v10
	s_waitcnt lgkmcnt(0)
	v_pk_mul_f32 v[12:13], v[16:17], v[12:13]
	s_nop 0
	v_cvt_pk_bf16_f32 v10, v12, v13
	v_lshlrev_b32_e32 v12, 16, v11
	v_and_b32_e32 v13, 0xffff0000, v11
	v_pk_mul_f32 v[12:13], v[18:19], v[12:13]
	s_nop 0
	v_cvt_pk_bf16_f32 v11, v12, v13
	global_store_dwordx4 v[2:3], v[8:11], off sc1
	v_add_u32_e32 v2, s38, v145
	v_ashrrev_i32_e32 v3, 31, v2
	v_mad_i64_i32 v[8:9], s[2:3], v2, s69, v[0:1]
	global_load_dwordx4 v[8:11], v[8:9], off
	ds_read_b128 v[12:15], v7
	ds_read_b128 v[16:19], v7 offset:16
	v_lshlrev_b64 v[2:3], 11, v[2:3]
	v_lshl_add_u64 v[2:3], v[4:5], 0, v[2:3]
	v_mad_i64_i32 v[0:1], s[2:3], v144, s69, v[0:1]
	v_ashrrev_i32_e32 v145, 31, v144
	s_waitcnt vmcnt(0)
	v_lshlrev_b32_e32 v20, 16, v8
	v_and_b32_e32 v21, 0xffff0000, v8
	s_waitcnt lgkmcnt(1)
	v_pk_mul_f32 v[12:13], v[12:13], v[20:21]
	s_nop 0
	v_cvt_pk_bf16_f32 v8, v12, v13
	v_lshlrev_b32_e32 v12, 16, v9
	v_and_b32_e32 v13, 0xffff0000, v9
	v_pk_mul_f32 v[12:13], v[14:15], v[12:13]
	s_nop 0
	v_cvt_pk_bf16_f32 v9, v12, v13
	v_lshlrev_b32_e32 v12, 16, v10
	v_and_b32_e32 v13, 0xffff0000, v10
	s_waitcnt lgkmcnt(0)
	v_pk_mul_f32 v[12:13], v[16:17], v[12:13]
	s_nop 0
	v_cvt_pk_bf16_f32 v10, v12, v13
	v_lshlrev_b32_e32 v12, 16, v11
	v_and_b32_e32 v13, 0xffff0000, v11
	v_pk_mul_f32 v[12:13], v[18:19], v[12:13]
	s_nop 0
	v_cvt_pk_bf16_f32 v11, v12, v13
	global_store_dwordx4 v[2:3], v[8:11], off sc1
	global_load_dwordx4 v[0:3], v[0:1], off
	s_waitcnt vmcnt(0)
	v_lshlrev_b32_e32 v14, 16, v0
	v_lshl_add_u32 v10, v147, 9, v6
	ds_read_b128 v[6:9], v10
	ds_read_b128 v[10:13], v10 offset:16
	v_and_b32_e32 v15, 0xffff0000, v0
	s_waitcnt lgkmcnt(1)
	v_pk_mul_f32 v[6:7], v[6:7], v[14:15]
	s_nop 0
	v_cvt_pk_bf16_f32 v0, v6, v7
	v_lshlrev_b32_e32 v6, 16, v1
	v_and_b32_e32 v7, 0xffff0000, v1
	v_pk_mul_f32 v[6:7], v[8:9], v[6:7]
	s_nop 0
	v_cvt_pk_bf16_f32 v1, v6, v7
	v_lshlrev_b32_e32 v6, 16, v2
	v_and_b32_e32 v7, 0xffff0000, v2
	s_waitcnt lgkmcnt(0)
	v_pk_mul_f32 v[6:7], v[10:11], v[6:7]
	s_nop 0
	v_cvt_pk_bf16_f32 v2, v6, v7
	v_lshlrev_b32_e32 v6, 16, v3
	v_and_b32_e32 v7, 0xffff0000, v3
	v_pk_mul_f32 v[6:7], v[12:13], v[6:7]
	s_nop 0
	v_cvt_pk_bf16_f32 v3, v6, v7
.LBB0_214:
	s_waitcnt vmcnt(0)
	v_lshlrev_b64 v[6:7], 11, v[144:145]
	s_add_i32 s49, s49, s52
	s_add_i32 s48, s48, s52
	v_lshl_add_u64 v[4:5], v[4:5], 0, v[6:7]
	s_cmpk_gt_i32 s49, 0x13ff
	s_waitcnt lgkmcnt(0)
	global_store_dwordx4 v[4:5], v[0:3], off sc1
	s_cbranch_scc1 .LBB0_229

.LBB0_221:
	ds_bpermute_b32 v32, v194, v171
	s_lshl_b64 s[2:3], s[8:9], 11
	s_add_u32 s2, s79, s2
	s_addc_u32 s3, s80, s3
	s_lshl_b32 s6, s6, 1
	s_waitcnt lgkmcnt(0)
	v_add_f32_e32 v32, v171, v32
	s_add_u32 s2, s2, s6
	v_div_scale_f32 v33, s[6:7], v32, v32, 1.0
	v_rcp_f32_e32 v34, v33
	s_movk_i32 s6, 0x50
	s_addc_u32 s3, s3, 0
	v_lshlrev_b32_e32 v158, 1, v150
	v_fma_f32 v35, -v33, v34, 1.0
	v_fmac_f32_e32 v34, v35, v34
	v_div_scale_f32 v35, vcc, 1.0, v32, 1.0
	v_mul_f32_e32 v36, v35, v34
	v_fma_f32 v37, -v33, v36, v35
	v_fmac_f32_e32 v36, v37, v34
	v_fma_f32 v33, -v33, v36, v35
	v_div_fmas_f32 v33, v33, v34, v36
	v_div_fixup_f32 v32, v33, v32, 1.0
	v_ashrrev_i32_e32 v33, 2, v207
	v_and_b32_e32 v33, -8, v33
	v_add_u32_e32 v33, v170, v33
	v_pk_mul_f32 v[0:1], v[0:1], v[32:33] op_sel_hi:[1,0]
	v_pk_mul_f32 v[2:3], v[2:3], v[32:33] op_sel_hi:[1,0]
	v_pk_mul_f32 v[16:17], v[16:17], v[32:33] op_sel_hi:[1,0]
	v_pk_mul_f32 v[18:19], v[18:19], v[32:33] op_sel_hi:[1,0]
	v_cvt_pk_bf16_f32 v0, v0, v1
	v_cvt_pk_bf16_f32 v1, v2, v3
	v_lshlrev_b32_e32 v2, 4, v206
	v_cvt_pk_bf16_f32 v16, v16, v17
	v_cvt_pk_bf16_f32 v17, v18, v19
	v_and_b32_e32 v18, 0x70, v2
	v_add_u32_e32 v2, v33, v18
	ds_write_b64 v2, v[16:17]
	v_xad_u32 v2, v18, 64, v33
	ds_write_b64 v2, v[0:1]
	v_pk_mul_f32 v[0:1], v[20:21], v[32:33] op_sel_hi:[1,0]
	v_pk_mul_f32 v[2:3], v[22:23], v[32:33] op_sel_hi:[1,0]
	v_cvt_pk_bf16_f32 v0, v0, v1
	v_cvt_pk_bf16_f32 v1, v2, v3
	v_pk_mul_f32 v[2:3], v[4:5], v[32:33] op_sel_hi:[1,0]
	v_pk_mul_f32 v[4:5], v[6:7], v[32:33] op_sel_hi:[1,0]
	v_cvt_pk_bf16_f32 v2, v2, v3
	v_cvt_pk_bf16_f32 v3, v4, v5
	v_xad_u32 v4, v18, 16, v33
	ds_write_b64 v4, v[0:1]
	v_xad_u32 v0, v18, s6, v33
	ds_write_b64 v0, v[2:3]
	v_pk_mul_f32 v[0:1], v[24:25], v[32:33] op_sel_hi:[1,0]
	v_pk_mul_f32 v[2:3], v[26:27], v[32:33] op_sel_hi:[1,0]
	v_cvt_pk_bf16_f32 v0, v0, v1
	v_cvt_pk_bf16_f32 v1, v2, v3
	v_pk_mul_f32 v[2:3], v[8:9], v[32:33] op_sel_hi:[1,0]
	v_pk_mul_f32 v[4:5], v[10:11], v[32:33] op_sel_hi:[1,0]
	v_cvt_pk_bf16_f32 v2, v2, v3
	v_cvt_pk_bf16_f32 v3, v4, v5
	v_xad_u32 v4, v18, 32, v33
	s_movk_i32 s6, 0x60
	ds_write_b64 v4, v[0:1]
	v_xad_u32 v0, v18, s6, v33
	ds_write_b64 v0, v[2:3]
	v_pk_mul_f32 v[0:1], v[28:29], v[32:33] op_sel_hi:[1,0]
	v_pk_mul_f32 v[2:3], v[30:31], v[32:33] op_sel_hi:[1,0]
	v_cvt_pk_bf16_f32 v0, v0, v1
	v_cvt_pk_bf16_f32 v1, v2, v3
	v_pk_mul_f32 v[2:3], v[12:13], v[32:33] op_sel_hi:[1,0]
	v_pk_mul_f32 v[4:5], v[14:15], v[32:33] op_sel_hi:[1,0]
	v_cvt_pk_bf16_f32 v2, v2, v3
	v_cvt_pk_bf16_f32 v3, v4, v5
	v_xad_u32 v4, v18, 48, v33
	s_movk_i32 s6, 0x70
	ds_write_b64 v4, v[0:1]
	v_xad_u32 v0, v18, s6, v33
	ds_write_b64 v0, v[2:3]
	ds_read_b128 v[0:3], v151
	v_lshl_add_u64 v[6:7], s[2:3], 0, v[158:159]
	v_lshlrev_b64 v[8:9], 11, v[148:149]
	v_lshl_add_u64 v[8:9], v[6:7], 0, v[8:9]
	s_mov_b64 s[2:3], 0x600
	s_waitcnt lgkmcnt(0)
	global_store_dwordx4 v[8:9], v[0:3], off offset:1536 sc1
	ds_read_b128 v[0:3], v147
	v_ashrrev_i32_e32 v147, 31, v146
	v_lshlrev_b64 v[8:9], 11, v[146:147]
	v_lshl_add_u64 v[8:9], v[6:7], 0, v[8:9]
	v_lshl_add_u64 v[4:5], v[6:7], 0, s[2:3]
	s_waitcnt lgkmcnt(0)
	global_store_dwordx4 v[8:9], v[0:3], off offset:1536 sc1
	v_add_u32_e32 v8, 16, v148
	v_ashrrev_i32_e32 v9, 31, v8
	v_lshlrev_b32_e32 v0, 7, v8
	v_add3_u32 v0, s33, v0, v145
	ds_read_b128 v[0:3], v0
	v_lshlrev_b64 v[8:9], 11, v[8:9]
	v_lshl_add_u64 v[6:7], v[6:7], 0, v[8:9]
	v_ashrrev_i32_e32 v145, 31, v144
	s_mov_b64 s[2:3], 0
	s_waitcnt lgkmcnt(0)
	global_store_dwordx4 v[6:7], v[0:3], off offset:1536 sc1
	ds_read_b128 v[0:3], v169

.LBB0_258:
	s_lshl_b32 s35, s93, 8
	v_mov_b32_e32 v138, v140
	v_mov_b32_e32 v139, v141
	s_or_b32 s35, s35, s86
	s_andn2_b64 vcc, exec, s[38:39]
	v_lshl_add_u32 v144, v139, 3, s35
	s_lshl_b32 s35, s92, 10
	v_add_u32_e32 v138, s85, v138
	s_add_i32 s35, s35, 0
	v_and_b32_e32 v139, 0xff, v138
	s_add_i32 s35, s35, 0x21400
	v_lshl_add_u32 v139, v139, 2, s35
	ds_read_b32 v146, v139
	v_lshl_add_u32 v138, s91, 8, v138
	v_ashrrev_i32_e32 v139, 31, v138
	v_ashrrev_i32_e32 v145, 31, v144
	v_lshlrev_b64 v[148:149], 11, v[138:139]
	s_waitcnt lgkmcnt(0)
	v_pk_mul_f32 v[126:127], v[126:127], v[146:147] op_sel_hi:[1,0]
	v_pk_mul_f32 v[124:125], v[124:125], v[146:147] op_sel_hi:[1,0]
	v_pk_mul_f32 v[120:121], v[120:121], v[146:147] op_sel_hi:[1,0]
	v_pk_mul_f32 v[150:151], v[122:123], v[146:147] op_sel_hi:[1,0]
	v_cvt_pk_bf16_f32 v122, v124, v125
	v_cvt_pk_bf16_f32 v123, v126, v127
	v_cvt_pk_bf16_f32 v124, v120, v121
	v_lshl_add_u64 v[126:127], s[36:37], 0, v[148:149]
	v_lshlrev_b64 v[120:121], 1, v[144:145]
	v_cvt_pk_bf16_f32 v125, v150, v151
	v_lshl_add_u64 v[126:127], v[126:127], 0, v[120:121]
	v_pk_mul_f32 v[116:117], v[116:117], v[146:147] op_sel_hi:[1,0]
	global_store_dwordx4 v[126:127], v[122:125], off sc1
	v_pk_mul_f32 v[118:119], v[118:119], v[146:147] op_sel_hi:[1,0]
	s_mov_b64 s[38:39], -1
	v_pk_mul_f32 v[122:123], v[114:115], v[146:147] op_sel_hi:[1,0]
	v_pk_mul_f32 v[114:115], v[112:113], v[146:147] op_sel_hi:[1,0]
	v_cvt_pk_bf16_f32 v112, v116, v117
	v_add_u32_e32 v116, 16, v138
	v_cvt_pk_bf16_f32 v114, v114, v115
	v_and_b32_e32 v115, 0xff, v116
	v_lshl_add_u32 v115, v115, 2, s35
	v_cvt_pk_bf16_f32 v113, v118, v119
	ds_read_b32 v118, v115
	v_cvt_pk_bf16_f32 v115, v122, v123
	v_ashrrev_i32_e32 v117, 31, v116
	global_store_dwordx4 v[126:127], v[112:115], off offset:256 sc1
	s_waitcnt lgkmcnt(0)
	v_pk_mul_f32 v[108:109], v[108:109], v[118:119] op_sel_hi:[1,0]
	v_lshlrev_b64 v[112:113], 11, v[116:117]
	v_pk_mul_f32 v[110:111], v[110:111], v[118:119] op_sel_hi:[1,0]
	v_pk_mul_f32 v[114:115], v[106:107], v[118:119] op_sel_hi:[1,0]
	v_pk_mul_f32 v[106:107], v[104:105], v[118:119] op_sel_hi:[1,0]
	v_cvt_pk_bf16_f32 v104, v108, v109
	v_lshl_add_u64 v[108:109], s[36:37], 0, v[112:113]
	v_cvt_pk_bf16_f32 v105, v110, v111
	v_cvt_pk_bf16_f32 v106, v106, v107
	v_cvt_pk_bf16_f32 v107, v114, v115
	v_lshl_add_u64 v[108:109], v[108:109], 0, v[120:121]
	v_pk_mul_f32 v[100:101], v[100:101], v[118:119] op_sel_hi:[1,0]
	global_store_dwordx4 v[108:109], v[104:107], off sc1
	v_pk_mul_f32 v[102:103], v[102:103], v[118:119] op_sel_hi:[1,0]
	s_nop 0
	v_pk_mul_f32 v[104:105], v[98:99], v[118:119] op_sel_hi:[1,0]
	v_pk_mul_f32 v[98:99], v[96:97], v[118:119] op_sel_hi:[1,0]
	v_cvt_pk_bf16_f32 v96, v100, v101
	v_add_u32_e32 v100, 32, v138
	v_cvt_pk_bf16_f32 v98, v98, v99
	v_and_b32_e32 v99, 0xff, v100
	v_lshl_add_u32 v99, v99, 2, s35
	v_cvt_pk_bf16_f32 v97, v102, v103
	ds_read_b32 v102, v99
	v_cvt_pk_bf16_f32 v99, v104, v105
	v_ashrrev_i32_e32 v101, 31, v100
	global_store_dwordx4 v[108:109], v[96:99], off offset:256 sc1
	s_waitcnt lgkmcnt(0)
	v_pk_mul_f32 v[92:93], v[92:93], v[102:103] op_sel_hi:[1,0]
	v_lshlrev_b64 v[96:97], 11, v[100:101]
	v_pk_mul_f32 v[94:95], v[94:95], v[102:103] op_sel_hi:[1,0]
	v_pk_mul_f32 v[98:99], v[90:91], v[102:103] op_sel_hi:[1,0]
	v_pk_mul_f32 v[90:91], v[88:89], v[102:103] op_sel_hi:[1,0]
	v_cvt_pk_bf16_f32 v88, v92, v93
	v_lshl_add_u64 v[92:93], s[36:37], 0, v[96:97]
	v_cvt_pk_bf16_f32 v89, v94, v95
	v_cvt_pk_bf16_f32 v90, v90, v91
	v_cvt_pk_bf16_f32 v91, v98, v99
	v_lshl_add_u64 v[92:93], v[92:93], 0, v[120:121]
	v_pk_mul_f32 v[84:85], v[84:85], v[102:103] op_sel_hi:[1,0]
	global_store_dwordx4 v[92:93], v[88:91], off sc1
	v_pk_mul_f32 v[86:87], v[86:87], v[102:103] op_sel_hi:[1,0]
	s_nop 0
	v_pk_mul_f32 v[88:89], v[82:83], v[102:103] op_sel_hi:[1,0]
	v_pk_mul_f32 v[82:83], v[80:81], v[102:103] op_sel_hi:[1,0]
	v_cvt_pk_bf16_f32 v80, v84, v85
	v_add_u32_e32 v84, 48, v138
	v_cvt_pk_bf16_f32 v82, v82, v83
	v_and_b32_e32 v83, 0xff, v84
	v_lshl_add_u32 v83, v83, 2, s35
	v_cvt_pk_bf16_f32 v81, v86, v87
	ds_read_b32 v86, v83
	v_cvt_pk_bf16_f32 v83, v88, v89
	v_ashrrev_i32_e32 v85, 31, v84
	global_store_dwordx4 v[92:93], v[80:83], off offset:256 sc1
	s_waitcnt lgkmcnt(0)
	v_pk_mul_f32 v[76:77], v[76:77], v[86:87] op_sel_hi:[1,0]
	v_lshlrev_b64 v[80:81], 11, v[84:85]
	v_pk_mul_f32 v[78:79], v[78:79], v[86:87] op_sel_hi:[1,0]
	v_pk_mul_f32 v[82:83], v[74:75], v[86:87] op_sel_hi:[1,0]
	v_pk_mul_f32 v[74:75], v[72:73], v[86:87] op_sel_hi:[1,0]
	v_cvt_pk_bf16_f32 v72, v76, v77
	v_lshl_add_u64 v[76:77], s[36:37], 0, v[80:81]
	v_cvt_pk_bf16_f32 v73, v78, v79
	v_cvt_pk_bf16_f32 v74, v74, v75
	v_cvt_pk_bf16_f32 v75, v82, v83
	v_lshl_add_u64 v[76:77], v[76:77], 0, v[120:121]
	v_pk_mul_f32 v[68:69], v[68:69], v[86:87] op_sel_hi:[1,0]
	global_store_dwordx4 v[76:77], v[72:75], off sc1
	v_pk_mul_f32 v[70:71], v[70:71], v[86:87] op_sel_hi:[1,0]
	s_nop 0
	v_pk_mul_f32 v[72:73], v[66:67], v[86:87] op_sel_hi:[1,0]
	v_pk_mul_f32 v[66:67], v[64:65], v[86:87] op_sel_hi:[1,0]
	v_cvt_pk_bf16_f32 v64, v68, v69
	v_add_u32_e32 v68, 0x80, v138
	v_cvt_pk_bf16_f32 v66, v66, v67
	v_and_b32_e32 v67, 0xff, v68
	v_lshl_add_u32 v67, v67, 2, s35
	v_cvt_pk_bf16_f32 v65, v70, v71
	ds_read_b32 v70, v67
	v_cvt_pk_bf16_f32 v67, v72, v73
	v_ashrrev_i32_e32 v69, 31, v68
	global_store_dwordx4 v[76:77], v[64:67], off offset:256 sc1
	s_waitcnt lgkmcnt(0)
	v_pk_mul_f32 v[60:61], v[60:61], v[70:71] op_sel_hi:[1,0]
	v_lshlrev_b64 v[64:65], 11, v[68:69]
	v_pk_mul_f32 v[62:63], v[62:63], v[70:71] op_sel_hi:[1,0]
	v_pk_mul_f32 v[66:67], v[58:59], v[70:71] op_sel_hi:[1,0]
	v_pk_mul_f32 v[58:59], v[56:57], v[70:71] op_sel_hi:[1,0]
	v_cvt_pk_bf16_f32 v56, v60, v61
	v_lshl_add_u64 v[60:61], s[36:37], 0, v[64:65]
	v_cvt_pk_bf16_f32 v57, v62, v63
	v_cvt_pk_bf16_f32 v58, v58, v59
	v_cvt_pk_bf16_f32 v59, v66, v67
	v_lshl_add_u64 v[60:61], v[60:61], 0, v[120:121]
	v_pk_mul_f32 v[52:53], v[52:53], v[70:71] op_sel_hi:[1,0]
	global_store_dwordx4 v[60:61], v[56:59], off sc1
	v_pk_mul_f32 v[54:55], v[54:55], v[70:71] op_sel_hi:[1,0]
	s_nop 0
	v_pk_mul_f32 v[56:57], v[50:51], v[70:71] op_sel_hi:[1,0]
	v_pk_mul_f32 v[50:51], v[48:49], v[70:71] op_sel_hi:[1,0]
	v_cvt_pk_bf16_f32 v48, v52, v53
	v_add_u32_e32 v52, 0x90, v138
	v_cvt_pk_bf16_f32 v50, v50, v51
	v_and_b32_e32 v51, 0xff, v52
	v_lshl_add_u32 v51, v51, 2, s35
	v_cvt_pk_bf16_f32 v49, v54, v55
	ds_read_b32 v54, v51
	v_cvt_pk_bf16_f32 v51, v56, v57
	v_ashrrev_i32_e32 v53, 31, v52
	global_store_dwordx4 v[60:61], v[48:51], off offset:256 sc1
	s_waitcnt lgkmcnt(0)
	v_pk_mul_f32 v[44:45], v[44:45], v[54:55] op_sel_hi:[1,0]
	v_lshlrev_b64 v[48:49], 11, v[52:53]
	v_pk_mul_f32 v[46:47], v[46:47], v[54:55] op_sel_hi:[1,0]
	v_pk_mul_f32 v[50:51], v[42:43], v[54:55] op_sel_hi:[1,0]
	v_pk_mul_f32 v[42:43], v[40:41], v[54:55] op_sel_hi:[1,0]
	v_cvt_pk_bf16_f32 v40, v44, v45
	v_lshl_add_u64 v[44:45], s[36:37], 0, v[48:49]
	v_cvt_pk_bf16_f32 v41, v46, v47
	v_cvt_pk_bf16_f32 v42, v42, v43
	v_cvt_pk_bf16_f32 v43, v50, v51
	v_lshl_add_u64 v[44:45], v[44:45], 0, v[120:121]
	v_pk_mul_f32 v[36:37], v[36:37], v[54:55] op_sel_hi:[1,0]
	global_store_dwordx4 v[44:45], v[40:43], off sc1
	v_pk_mul_f32 v[38:39], v[38:39], v[54:55] op_sel_hi:[1,0]
	s_nop 0
	v_pk_mul_f32 v[40:41], v[34:35], v[54:55] op_sel_hi:[1,0]
	v_pk_mul_f32 v[34:35], v[32:33], v[54:55] op_sel_hi:[1,0]
	v_cvt_pk_bf16_f32 v32, v36, v37
	v_add_u32_e32 v36, 0xa0, v138
	v_cvt_pk_bf16_f32 v34, v34, v35
	v_and_b32_e32 v35, 0xff, v36
	v_lshl_add_u32 v35, v35, 2, s35
	v_cvt_pk_bf16_f32 v33, v38, v39
	ds_read_b32 v38, v35
	v_cvt_pk_bf16_f32 v35, v40, v41
	v_ashrrev_i32_e32 v37, 31, v36
	global_store_dwordx4 v[44:45], v[32:35], off offset:256 sc1
	s_waitcnt lgkmcnt(0)
	v_pk_mul_f32 v[28:29], v[28:29], v[38:39] op_sel_hi:[1,0]
	v_lshlrev_b64 v[32:33], 11, v[36:37]
	v_pk_mul_f32 v[24:25], v[24:25], v[38:39] op_sel_hi:[1,0]
	v_pk_mul_f32 v[30:31], v[30:31], v[38:39] op_sel_hi:[1,0]
	v_pk_mul_f32 v[34:35], v[26:27], v[38:39] op_sel_hi:[1,0]
	v_cvt_pk_bf16_f32 v26, v28, v29
	v_cvt_pk_bf16_f32 v28, v24, v25
	v_lshl_add_u64 v[24:25], s[36:37], 0, v[32:33]
	v_cvt_pk_bf16_f32 v27, v30, v31
	v_cvt_pk_bf16_f32 v29, v34, v35
	v_lshl_add_u64 v[24:25], v[24:25], 0, v[120:121]
	v_pk_mul_f32 v[22:23], v[22:23], v[38:39] op_sel_hi:[1,0]
	global_store_dwordx4 v[24:25], v[26:29], off sc1
	v_pk_mul_f32 v[20:21], v[20:21], v[38:39] op_sel_hi:[1,0]
	s_nop 0
	v_pk_mul_f32 v[26:27], v[18:19], v[38:39] op_sel_hi:[1,0]
	v_pk_mul_f32 v[18:19], v[16:17], v[38:39] op_sel_hi:[1,0]
	v_cvt_pk_bf16_f32 v17, v22, v23
	v_add_u32_e32 v22, 0xb0, v138
	v_cvt_pk_bf16_f32 v18, v18, v19
	v_and_b32_e32 v19, 0xff, v22
	v_lshl_add_u32 v19, v19, 2, s35
	v_cvt_pk_bf16_f32 v16, v20, v21
	ds_read_b32 v20, v19
	v_cvt_pk_bf16_f32 v19, v26, v27
	v_ashrrev_i32_e32 v23, 31, v22
	global_store_dwordx4 v[24:25], v[16:19], off offset:256 sc1
	s_waitcnt lgkmcnt(0)
	v_pk_mul_f32 v[12:13], v[12:13], v[20:21] op_sel_hi:[1,0]
	v_lshlrev_b64 v[16:17], 11, v[22:23]
	v_pk_mul_f32 v[14:15], v[14:15], v[20:21] op_sel_hi:[1,0]
	v_pk_mul_f32 v[18:19], v[10:11], v[20:21] op_sel_hi:[1,0]
	v_pk_mul_f32 v[10:11], v[8:9], v[20:21] op_sel_hi:[1,0]
	v_cvt_pk_bf16_f32 v8, v12, v13
	v_lshl_add_u64 v[12:13], s[36:37], 0, v[16:17]
	v_cvt_pk_bf16_f32 v9, v14, v15
	v_cvt_pk_bf16_f32 v10, v10, v11
	v_cvt_pk_bf16_f32 v11, v18, v19
	v_lshl_add_u64 v[12:13], v[12:13], 0, v[120:121]
	global_store_dwordx4 v[12:13], v[8:11], off sc1
	v_pk_mul_f32 v[6:7], v[6:7], v[20:21] op_sel_hi:[1,0]
	v_pk_mul_f32 v[4:5], v[4:5], v[20:21] op_sel_hi:[1,0]
	v_pk_mul_f32 v[8:9], v[2:3], v[20:21] op_sel_hi:[1,0]
	v_pk_mul_f32 v[2:3], v[0:1], v[20:21] op_sel_hi:[1,0]
	v_cvt_pk_bf16_f32 v0, v4, v5
	v_cvt_pk_bf16_f32 v1, v6, v7
	v_cvt_pk_bf16_f32 v2, v2, v3
	v_cvt_pk_bf16_f32 v3, v8, v9
	global_store_dwordx4 v[12:13], v[0:3], off offset:256 sc1
	s_cbranch_vccnz .LBB0_247
	s_andn2_b64 vcc, exec, s[16:17]
	s_cbranch_vccnz .LBB0_246
	s_barrier
	s_branch .LBB0_246

.LBB0_285:
	v_lshl_add_u32 v120, s46, 8, v141
	v_ashrrev_i32_e32 v124, 13, v120
	v_bfe_u32 v125, v120, 7, 6
	v_lshl_or_b32 v124, v124, 6, v125
	s_cmp_gt_i32 s93, 2
	v_lshl_add_u32 v122, v170, 3, s88
	v_ashrrev_i32_e32 v121, 31, v120
	v_mad_i64_i32 v[124:125], s[42:43], v124, s67, 0
	s_cselect_b64 s[48:49], -1, 0
	v_ashrrev_i32_e32 v123, 31, v122
	v_add_u32_e32 v168, 0xfffffd00, v122
	v_lshlrev_b64 v[126:127], 9, v[120:121]
	v_and_b32_e32 v169, 0x7f, v141
	s_mov_b64 s[42:43], -1
	s_and_b64 vcc, exec, s[48:49]
	s_cbranch_vccz .LBB0_291
	s_and_b64 vcc, exec, s[40:41]
	s_cbranch_vccz .LBB0_288
	v_lshl_add_u64 v[142:143], s[4:5], 0, v[126:127]
	v_cvt_pk_bf16_f32 v172, v144, v145
	v_cvt_pk_bf16_f32 v173, v146, v147
	v_cvt_pk_bf16_f32 v174, v148, v149
	v_cvt_pk_bf16_f32 v175, v150, v151
	v_lshl_add_u64 v[142:143], v[122:123], 1, v[142:143]
	global_store_dwordx4 v[142:143], v[172:175], off sc1
	s_mov_b64 s[42:43], 0

.LBB0_291:
	v_mad_i64_i32 v[142:143], s[46:47], v120, s69, 0
	s_andn2_b64 vcc, exec, s[42:43]
	v_lshl_add_u64 v[142:143], s[36:37], 0, v[142:143]
	s_cbranch_vccnz .LBB0_293
	s_lshl_b32 s42, s93, 8
	s_ashr_i32 s43, s42, 31
	v_cvt_pk_bf16_f32 v144, v144, v145
	v_cvt_pk_bf16_f32 v145, v146, v147
	v_cvt_pk_bf16_f32 v146, v148, v149
	v_lshl_add_u64 v[148:149], s[42:43], 1, v[142:143]
	v_cvt_pk_bf16_f32 v147, v150, v151
	v_lshl_add_u64 v[148:149], v[122:123], 1, v[148:149]
	v_mov_b32_e32 v171, 0
	global_store_dwordx4 v[148:149], v[144:147], off sc1

.LBB0_295:
	v_cndmask_b32_e64 v140, 0, 1, s[48:49]
	v_cmp_ne_u32_e64 s[46:47], 1, v140
	v_cndmask_b32_e64 v140, 0, 1, s[40:41]
	s_mov_b64 s[44:45], -1
	s_andn2_b64 vcc, exec, s[48:49]
	v_cmp_ne_u32_e64 s[40:41], 1, v140
	s_cbranch_vccnz .LBB0_301
	s_and_b64 vcc, exec, s[40:41]
	s_cbranch_vccnz .LBB0_298
	v_lshl_add_u64 v[126:127], s[4:5], 0, v[126:127]
	v_cvt_pk_bf16_f32 v144, v116, v117
	v_cvt_pk_bf16_f32 v145, v118, v119
	v_cvt_pk_bf16_f32 v146, v112, v113
	v_cvt_pk_bf16_f32 v147, v114, v115
	v_lshl_add_u64 v[126:127], v[122:123], 1, v[126:127]
	s_mov_b64 s[44:45], 0
	global_store_dwordx4 v[126:127], v[144:147], off offset:256 sc1

.LBB0_301:
	s_andn2_b64 vcc, exec, s[44:45]
	s_cbranch_vccnz .LBB0_303
	s_lshl_b32 s44, s93, 8
	s_ashr_i32 s45, s44, 31
	v_cvt_pk_bf16_f32 v116, v116, v117
	v_cvt_pk_bf16_f32 v117, v118, v119
	v_cvt_pk_bf16_f32 v118, v112, v113
	v_lshl_add_u64 v[112:113], s[44:45], 1, v[142:143]
	v_cvt_pk_bf16_f32 v119, v114, v115
	v_lshl_add_u64 v[112:113], v[122:123], 1, v[112:113]
	v_mov_b32_e32 v140, v171
	global_store_dwordx4 v[112:113], v[116:119], off offset:256 sc1

.LBB0_309:
	v_ashrrev_i32_e32 v104, 13, v114
	v_bfe_u32 v105, v114, 7, 6
	v_lshl_or_b32 v104, v104, 6, v105
	v_ashrrev_i32_e32 v115, 31, v114
	v_mad_i64_i32 v[104:105], s[48:49], v104, s67, 0
	v_lshlrev_b64 v[106:107], 9, v[114:115]
	v_and_b32_e32 v115, 0x7f, v114
	s_and_b64 vcc, exec, s[46:47]
	s_mov_b64 s[48:49], -1
	s_cbranch_vccnz .LBB0_315
	s_and_b64 vcc, exec, s[40:41]
	s_cbranch_vccnz .LBB0_312
	v_lshl_add_u64 v[108:109], s[4:5], 0, v[106:107]
	v_cvt_pk_bf16_f32 v140, v124, v125
	v_cvt_pk_bf16_f32 v141, v110, v111
	v_cvt_pk_bf16_f32 v142, v116, v117
	v_cvt_pk_bf16_f32 v143, v118, v119
	v_lshl_add_u64 v[108:109], v[122:123], 1, v[108:109]
	s_mov_b64 s[48:49], 0
	global_store_dwordx4 v[108:109], v[140:143], off sc1

.LBB0_315:
	v_mad_i64_i32 v[108:109], s[62:63], v114, s69, 0
	s_andn2_b64 vcc, exec, s[48:49]
	v_lshl_add_u64 v[108:109], s[36:37], 0, v[108:109]
	s_cbranch_vccnz .LBB0_317
	s_lshl_b32 s48, s93, 8
	s_ashr_i32 s49, s48, 31
	v_cvt_pk_bf16_f32 v124, v124, v125
	v_cvt_pk_bf16_f32 v125, v110, v111
	v_lshl_add_u64 v[110:111], s[48:49], 1, v[108:109]
	v_cvt_pk_bf16_f32 v126, v116, v117
	v_cvt_pk_bf16_f32 v127, v118, v119
	v_lshl_add_u64 v[110:111], v[122:123], 1, v[110:111]
	global_store_dwordx4 v[110:111], v[124:127], off sc1
	s_nop 1
	v_mov_b32_e32 v126, 0

.LBB0_322:
	s_and_b64 vcc, exec, s[40:41]
	s_cbranch_vccnz .LBB0_324
	v_lshl_add_u64 v[106:107], s[4:5], 0, v[106:107]
	v_cvt_pk_bf16_f32 v110, v100, v101
	v_cvt_pk_bf16_f32 v111, v102, v103
	v_cvt_pk_bf16_f32 v112, v96, v97
	v_cvt_pk_bf16_f32 v113, v98, v99
	v_lshl_add_u64 v[106:107], v[122:123], 1, v[106:107]
	s_mov_b64 s[48:49], 0
	global_store_dwordx4 v[106:107], v[110:113], off offset:256 sc1

.LBB0_327:
	s_lshl_b32 s48, s93, 8
	s_ashr_i32 s49, s48, 31
	v_cvt_pk_bf16_f32 v100, v100, v101
	v_cvt_pk_bf16_f32 v101, v102, v103
	v_cvt_pk_bf16_f32 v102, v96, v97
	v_lshl_add_u64 v[96:97], s[48:49], 1, v[108:109]
	v_cvt_pk_bf16_f32 v103, v98, v99
	v_lshl_add_u64 v[96:97], v[122:123], 1, v[96:97]
	v_mov_b32_e32 v110, v126
	global_store_dwordx4 v[96:97], v[100:103], off offset:256 sc1
	v_cndmask_b32_e64 v96, 0, 1, s[64:65]
	v_cmp_ne_u32_e64 s[48:49], 1, v96
	s_andn2_b64 vcc, exec, s[64:65]
	s_cbranch_vccnz .LBB0_331

.LBB0_333:
	v_ashrrev_i32_e32 v88, 13, v98
	v_bfe_u32 v89, v98, 7, 6
	v_ashrrev_i32_e32 v99, 31, v98
	v_lshl_or_b32 v88, v88, 6, v89
	v_lshlrev_b64 v[90:91], 9, v[98:99]
	v_mad_i64_i32 v[88:89], s[62:63], v88, s67, 0
	v_and_b32_e32 v99, 0x7f, v98
	s_and_b64 vcc, exec, s[46:47]
	s_mov_b64 s[64:65], -1
	s_cbranch_vccnz .LBB0_339
	s_and_b64 vcc, exec, s[40:41]
	s_cbranch_vccnz .LBB0_336
	v_lshl_add_u64 v[92:93], s[4:5], 0, v[90:91]
	v_cvt_pk_bf16_f32 v106, v104, v105
	v_cvt_pk_bf16_f32 v107, v94, v95
	v_cvt_pk_bf16_f32 v108, v100, v101
	v_cvt_pk_bf16_f32 v109, v102, v103
	v_lshl_add_u64 v[92:93], v[122:123], 1, v[92:93]
	s_mov_b64 s[64:65], 0
	global_store_dwordx4 v[92:93], v[106:109], off sc1

.LBB0_339:
	v_mad_i64_i32 v[92:93], s[62:63], v98, s69, 0
	s_andn2_b64 vcc, exec, s[64:65]
	v_lshl_add_u64 v[92:93], s[36:37], 0, v[92:93]
	s_cbranch_vccnz .LBB0_341
	s_lshl_b32 s62, s93, 8
	s_ashr_i32 s63, s62, 31
	v_cvt_pk_bf16_f32 v104, v104, v105
	v_cvt_pk_bf16_f32 v105, v94, v95
	v_lshl_add_u64 v[94:95], s[62:63], 1, v[92:93]
	v_cvt_pk_bf16_f32 v106, v100, v101
	v_cvt_pk_bf16_f32 v107, v102, v103
	v_lshl_add_u64 v[94:95], v[122:123], 1, v[94:95]
	global_store_dwordx4 v[94:95], v[104:107], off sc1
	s_nop 1
	v_mov_b32_e32 v106, 0

.LBB0_346:
	s_and_b64 vcc, exec, s[40:41]
	s_cbranch_vccnz .LBB0_348
	v_lshl_add_u64 v[90:91], s[4:5], 0, v[90:91]
	v_cvt_pk_bf16_f32 v94, v84, v85
	v_cvt_pk_bf16_f32 v95, v86, v87
	v_cvt_pk_bf16_f32 v96, v80, v81
	v_cvt_pk_bf16_f32 v97, v82, v83
	v_lshl_add_u64 v[90:91], v[122:123], 1, v[90:91]
	s_mov_b64 s[64:65], 0
	global_store_dwordx4 v[90:91], v[94:97], off offset:256 sc1

.LBB0_351:
	s_lshl_b32 s62, s93, 8
	s_ashr_i32 s63, s62, 31
	v_cvt_pk_bf16_f32 v84, v84, v85
	v_cvt_pk_bf16_f32 v85, v86, v87
	v_cvt_pk_bf16_f32 v86, v80, v81
	v_lshl_add_u64 v[80:81], s[62:63], 1, v[92:93]
	v_cvt_pk_bf16_f32 v87, v82, v83
	v_lshl_add_u64 v[80:81], v[122:123], 1, v[80:81]
	v_mov_b32_e32 v94, v106
	global_store_dwordx4 v[80:81], v[84:87], off offset:256 sc1
	s_and_b64 vcc, exec, s[48:49]
	s_cbranch_vccnz .LBB0_355

.LBB0_357:
	v_ashrrev_i32_e32 v72, 13, v82
	v_bfe_u32 v73, v82, 7, 6
	v_ashrrev_i32_e32 v83, 31, v82
	v_lshl_or_b32 v72, v72, 6, v73
	v_lshlrev_b64 v[74:75], 9, v[82:83]
	v_mad_i64_i32 v[72:73], s[62:63], v72, s67, 0
	v_and_b32_e32 v83, 0x7f, v82
	s_and_b64 vcc, exec, s[46:47]
	s_mov_b64 s[64:65], -1
	s_cbranch_vccnz .LBB0_363
	s_and_b64 vcc, exec, s[40:41]
	s_cbranch_vccnz .LBB0_360
	v_lshl_add_u64 v[76:77], s[4:5], 0, v[74:75]
	v_cvt_pk_bf16_f32 v90, v88, v89
	v_cvt_pk_bf16_f32 v91, v78, v79
	v_cvt_pk_bf16_f32 v92, v84, v85
	v_cvt_pk_bf16_f32 v93, v86, v87
	v_lshl_add_u64 v[76:77], v[122:123], 1, v[76:77]
	s_mov_b64 s[64:65], 0
	global_store_dwordx4 v[76:77], v[90:93], off sc1

.LBB0_363:
	v_mad_i64_i32 v[76:77], s[62:63], v82, s69, 0
	s_andn2_b64 vcc, exec, s[64:65]
	v_lshl_add_u64 v[76:77], s[36:37], 0, v[76:77]
	s_cbranch_vccnz .LBB0_365
	s_lshl_b32 s62, s93, 8
	s_ashr_i32 s63, s62, 31
	v_cvt_pk_bf16_f32 v88, v88, v89
	v_cvt_pk_bf16_f32 v89, v78, v79
	v_lshl_add_u64 v[78:79], s[62:63], 1, v[76:77]
	v_cvt_pk_bf16_f32 v90, v84, v85
	v_cvt_pk_bf16_f32 v91, v86, v87
	v_lshl_add_u64 v[78:79], v[122:123], 1, v[78:79]
	global_store_dwordx4 v[78:79], v[88:91], off sc1
	s_nop 1
	v_mov_b32_e32 v90, 0

.LBB0_370:
	s_and_b64 vcc, exec, s[40:41]
	s_cbranch_vccnz .LBB0_372
	v_lshl_add_u64 v[74:75], s[4:5], 0, v[74:75]
	v_cvt_pk_bf16_f32 v78, v68, v69
	v_cvt_pk_bf16_f32 v79, v70, v71
	v_cvt_pk_bf16_f32 v80, v64, v65
	v_cvt_pk_bf16_f32 v81, v66, v67
	v_lshl_add_u64 v[74:75], v[122:123], 1, v[74:75]
	s_mov_b64 s[64:65], 0
	global_store_dwordx4 v[74:75], v[78:81], off offset:256 sc1

.LBB0_375:
	s_lshl_b32 s62, s93, 8
	s_ashr_i32 s63, s62, 31
	v_cvt_pk_bf16_f32 v68, v68, v69
	v_cvt_pk_bf16_f32 v69, v70, v71
	v_cvt_pk_bf16_f32 v70, v64, v65
	v_lshl_add_u64 v[64:65], s[62:63], 1, v[76:77]
	v_cvt_pk_bf16_f32 v71, v66, v67
	v_lshl_add_u64 v[64:65], v[122:123], 1, v[64:65]
	v_mov_b32_e32 v78, v90
	global_store_dwordx4 v[64:65], v[68:71], off offset:256 sc1
	s_and_b64 vcc, exec, s[48:49]
	s_cbranch_vccnz .LBB0_379

.LBB0_381:
	v_ashrrev_i32_e32 v56, 13, v66
	v_bfe_u32 v57, v66, 7, 6
	v_ashrrev_i32_e32 v67, 31, v66
	v_lshl_or_b32 v56, v56, 6, v57
	v_lshlrev_b64 v[58:59], 9, v[66:67]
	v_mad_i64_i32 v[56:57], s[62:63], v56, s67, 0
	s_and_b64 vcc, exec, s[46:47]
	s_mov_b64 s[64:65], -1
	s_cbranch_vccnz .LBB0_387
	s_and_b64 vcc, exec, s[40:41]
	s_cbranch_vccnz .LBB0_384
	v_lshl_add_u64 v[60:61], s[4:5], 0, v[58:59]
	v_cvt_pk_bf16_f32 v74, v72, v73
	v_cvt_pk_bf16_f32 v75, v62, v63
	v_cvt_pk_bf16_f32 v76, v68, v69
	v_cvt_pk_bf16_f32 v77, v70, v71
	v_lshl_add_u64 v[60:61], v[122:123], 1, v[60:61]
	s_mov_b64 s[64:65], 0
	global_store_dwordx4 v[60:61], v[74:77], off sc1

.LBB0_387:
	v_mad_i64_i32 v[60:61], s[62:63], v66, s69, 0
	s_andn2_b64 vcc, exec, s[64:65]
	v_lshl_add_u64 v[60:61], s[36:37], 0, v[60:61]
	s_cbranch_vccnz .LBB0_389
	s_lshl_b32 s62, s93, 8
	s_ashr_i32 s63, s62, 31
	v_cvt_pk_bf16_f32 v67, v62, v63
	v_lshl_add_u64 v[62:63], s[62:63], 1, v[60:61]
	v_cvt_pk_bf16_f32 v66, v72, v73
	v_cvt_pk_bf16_f32 v68, v68, v69
	v_cvt_pk_bf16_f32 v69, v70, v71
	v_lshl_add_u64 v[62:63], v[122:123], 1, v[62:63]
	global_store_dwordx4 v[62:63], v[66:69], off sc1
	s_nop 1
	v_mov_b32_e32 v67, 0

.LBB0_394:
	s_and_b64 vcc, exec, s[40:41]
	s_cbranch_vccnz .LBB0_396
	v_lshl_add_u64 v[58:59], s[4:5], 0, v[58:59]
	v_cvt_pk_bf16_f32 v62, v52, v53
	v_cvt_pk_bf16_f32 v63, v54, v55
	v_cvt_pk_bf16_f32 v64, v48, v49
	v_cvt_pk_bf16_f32 v65, v50, v51
	v_lshl_add_u64 v[58:59], v[122:123], 1, v[58:59]
	s_mov_b64 s[64:65], 0
	global_store_dwordx4 v[58:59], v[62:65], off offset:256 sc1

.LBB0_399:
	s_lshl_b32 s62, s93, 8
	s_ashr_i32 s63, s62, 31
	v_cvt_pk_bf16_f32 v52, v52, v53
	v_cvt_pk_bf16_f32 v53, v54, v55
	v_cvt_pk_bf16_f32 v54, v48, v49
	v_lshl_add_u64 v[48:49], s[62:63], 1, v[60:61]
	v_cvt_pk_bf16_f32 v55, v50, v51
	v_lshl_add_u64 v[48:49], v[122:123], 1, v[48:49]
	v_mov_b32_e32 v62, v67
	global_store_dwordx4 v[48:49], v[52:55], off offset:256 sc1
	s_and_b64 vcc, exec, s[48:49]
	s_cbranch_vccnz .LBB0_403

.LBB0_405:
	v_ashrrev_i32_e32 v40, 13, v50
	v_bfe_u32 v41, v50, 7, 6
	v_ashrrev_i32_e32 v51, 31, v50
	v_lshl_or_b32 v40, v40, 6, v41
	v_lshlrev_b64 v[42:43], 9, v[50:51]
	v_mad_i64_i32 v[40:41], s[62:63], v40, s67, 0
	v_and_b32_e32 v51, 0x7f, v50
	s_and_b64 vcc, exec, s[46:47]
	s_mov_b64 s[64:65], -1
	s_cbranch_vccnz .LBB0_411
	s_and_b64 vcc, exec, s[40:41]
	s_cbranch_vccnz .LBB0_408
	v_lshl_add_u64 v[44:45], s[4:5], 0, v[42:43]
	v_cvt_pk_bf16_f32 v58, v56, v57
	v_cvt_pk_bf16_f32 v59, v46, v47
	v_cvt_pk_bf16_f32 v60, v52, v53
	v_cvt_pk_bf16_f32 v61, v54, v55
	v_lshl_add_u64 v[44:45], v[122:123], 1, v[44:45]
	s_mov_b64 s[64:65], 0
	global_store_dwordx4 v[44:45], v[58:61], off sc1

.LBB0_411:
	v_mad_i64_i32 v[44:45], s[62:63], v50, s69, 0
	s_andn2_b64 vcc, exec, s[64:65]
	v_lshl_add_u64 v[44:45], s[36:37], 0, v[44:45]
	s_cbranch_vccnz .LBB0_413
	s_lshl_b32 s62, s93, 8
	s_ashr_i32 s63, s62, 31
	v_cvt_pk_bf16_f32 v56, v56, v57
	v_cvt_pk_bf16_f32 v57, v46, v47
	v_lshl_add_u64 v[46:47], s[62:63], 1, v[44:45]
	v_cvt_pk_bf16_f32 v58, v52, v53
	v_cvt_pk_bf16_f32 v59, v54, v55
	v_lshl_add_u64 v[46:47], v[122:123], 1, v[46:47]
	global_store_dwordx4 v[46:47], v[56:59], off sc1
	s_nop 1
	v_mov_b32_e32 v58, 0

.LBB0_418:
	s_and_b64 vcc, exec, s[40:41]
	s_cbranch_vccnz .LBB0_420
	v_lshl_add_u64 v[42:43], s[4:5], 0, v[42:43]
	v_cvt_pk_bf16_f32 v46, v36, v37
	v_cvt_pk_bf16_f32 v47, v38, v39
	v_cvt_pk_bf16_f32 v48, v32, v33
	v_cvt_pk_bf16_f32 v49, v34, v35
	v_lshl_add_u64 v[42:43], v[122:123], 1, v[42:43]
	s_mov_b64 s[64:65], 0
	global_store_dwordx4 v[42:43], v[46:49], off offset:256 sc1

.LBB0_423:
	s_lshl_b32 s62, s93, 8
	s_ashr_i32 s63, s62, 31
	v_cvt_pk_bf16_f32 v36, v36, v37
	v_cvt_pk_bf16_f32 v37, v38, v39
	v_cvt_pk_bf16_f32 v38, v32, v33
	v_lshl_add_u64 v[32:33], s[62:63], 1, v[44:45]
	v_cvt_pk_bf16_f32 v39, v34, v35
	v_lshl_add_u64 v[32:33], v[122:123], 1, v[32:33]
	v_mov_b32_e32 v46, v58
	global_store_dwordx4 v[32:33], v[36:39], off offset:256 sc1
	s_and_b64 vcc, exec, s[48:49]
	s_cbranch_vccnz .LBB0_427

.LBB0_429:
	v_ashrrev_i32_e32 v24, 13, v34
	v_bfe_u32 v25, v34, 7, 6
	v_ashrrev_i32_e32 v35, 31, v34
	v_lshl_or_b32 v24, v24, 6, v25
	v_lshlrev_b64 v[26:27], 9, v[34:35]
	v_mad_i64_i32 v[24:25], s[62:63], v24, s67, 0
	v_and_b32_e32 v35, 0x7f, v34
	s_and_b64 vcc, exec, s[46:47]
	s_mov_b64 s[64:65], -1
	s_cbranch_vccnz .LBB0_435
	s_and_b64 vcc, exec, s[40:41]
	s_cbranch_vccnz .LBB0_432
	v_lshl_add_u64 v[28:29], s[4:5], 0, v[26:27]
	v_cvt_pk_bf16_f32 v42, v40, v41
	v_cvt_pk_bf16_f32 v43, v30, v31
	v_cvt_pk_bf16_f32 v44, v36, v37
	v_cvt_pk_bf16_f32 v45, v38, v39
	v_lshl_add_u64 v[28:29], v[122:123], 1, v[28:29]
	s_mov_b64 s[64:65], 0
	global_store_dwordx4 v[28:29], v[42:45], off sc1

.LBB0_435:
	v_mad_i64_i32 v[28:29], s[62:63], v34, s69, 0
	s_andn2_b64 vcc, exec, s[64:65]
	v_lshl_add_u64 v[28:29], s[36:37], 0, v[28:29]
	s_cbranch_vccnz .LBB0_437
	s_lshl_b32 s62, s93, 8
	s_ashr_i32 s63, s62, 31
	v_cvt_pk_bf16_f32 v40, v40, v41
	v_cvt_pk_bf16_f32 v41, v30, v31
	v_lshl_add_u64 v[30:31], s[62:63], 1, v[28:29]
	v_cvt_pk_bf16_f32 v42, v36, v37
	v_cvt_pk_bf16_f32 v43, v38, v39
	v_lshl_add_u64 v[30:31], v[122:123], 1, v[30:31]
	global_store_dwordx4 v[30:31], v[40:43], off sc1
	s_nop 1
	v_mov_b32_e32 v42, 0

.LBB0_442:
	s_and_b64 vcc, exec, s[40:41]
	s_cbranch_vccnz .LBB0_444
	v_lshl_add_u64 v[26:27], s[4:5], 0, v[26:27]
	v_cvt_pk_bf16_f32 v30, v20, v21
	v_cvt_pk_bf16_f32 v31, v22, v23
	v_cvt_pk_bf16_f32 v32, v16, v17
	v_cvt_pk_bf16_f32 v33, v18, v19
	v_lshl_add_u64 v[26:27], v[122:123], 1, v[26:27]
	s_mov_b64 s[64:65], 0
	global_store_dwordx4 v[26:27], v[30:33], off offset:256 sc1

.LBB0_447:
	s_lshl_b32 s62, s93, 8
	s_ashr_i32 s63, s62, 31
	v_cvt_pk_bf16_f32 v20, v20, v21
	v_cvt_pk_bf16_f32 v21, v22, v23
	v_cvt_pk_bf16_f32 v22, v16, v17
	v_lshl_add_u64 v[16:17], s[62:63], 1, v[28:29]
	v_cvt_pk_bf16_f32 v23, v18, v19
	v_lshl_add_u64 v[16:17], v[122:123], 1, v[16:17]
	v_mov_b32_e32 v30, v42
	global_store_dwordx4 v[16:17], v[20:23], off offset:256 sc1
	s_and_b64 vcc, exec, s[48:49]
	s_cbranch_vccnz .LBB0_451

.LBB0_453:
	v_ashrrev_i32_e32 v8, 13, v18
	v_bfe_u32 v9, v18, 7, 6
	v_ashrrev_i32_e32 v19, 31, v18
	v_lshl_or_b32 v8, v8, 6, v9
	v_lshlrev_b64 v[10:11], 9, v[18:19]
	v_mad_i64_i32 v[8:9], s[62:63], v8, s67, 0
	v_and_b32_e32 v19, 0x7f, v18
	s_and_b64 vcc, exec, s[46:47]
	s_mov_b64 s[64:65], -1
	s_cbranch_vccnz .LBB0_459
	s_and_b64 vcc, exec, s[40:41]
	s_cbranch_vccnz .LBB0_456
	v_lshl_add_u64 v[12:13], s[4:5], 0, v[10:11]
	v_cvt_pk_bf16_f32 v26, v24, v25
	v_cvt_pk_bf16_f32 v27, v14, v15
	v_cvt_pk_bf16_f32 v28, v20, v21
	v_cvt_pk_bf16_f32 v29, v22, v23
	v_lshl_add_u64 v[12:13], v[122:123], 1, v[12:13]
	s_mov_b64 s[64:65], 0
	global_store_dwordx4 v[12:13], v[26:29], off sc1

.LBB0_459:
	v_mad_i64_i32 v[12:13], s[62:63], v18, s69, 0
	s_andn2_b64 vcc, exec, s[64:65]
	v_lshl_add_u64 v[12:13], s[36:37], 0, v[12:13]
	s_cbranch_vccnz .LBB0_461
	s_lshl_b32 s62, s93, 8
	s_ashr_i32 s63, s62, 31
	v_cvt_pk_bf16_f32 v24, v24, v25
	v_cvt_pk_bf16_f32 v25, v14, v15
	v_lshl_add_u64 v[14:15], s[62:63], 1, v[12:13]
	v_cvt_pk_bf16_f32 v26, v20, v21
	v_cvt_pk_bf16_f32 v27, v22, v23
	v_lshl_add_u64 v[14:15], v[122:123], 1, v[14:15]
	global_store_dwordx4 v[14:15], v[24:27], off sc1
	s_nop 1
	v_mov_b32_e32 v26, 0

.LBB0_467:
	s_and_b64 vcc, exec, s[40:41]
	s_mov_b64 s[40:41], -1
	s_cbranch_vccnz .LBB0_469
	v_lshl_add_u64 v[10:11], s[4:5], 0, v[10:11]
	v_cvt_pk_bf16_f32 v14, v4, v5
	v_cvt_pk_bf16_f32 v15, v6, v7
	v_cvt_pk_bf16_f32 v16, v0, v1
	v_cvt_pk_bf16_f32 v17, v2, v3
	v_lshl_add_u64 v[10:11], v[122:123], 1, v[10:11]
	s_mov_b64 s[40:41], 0
	global_store_dwordx4 v[10:11], v[14:17], off offset:256 sc1

.LBB0_472:
	s_lshl_b32 s40, s93, 8
	s_ashr_i32 s41, s40, 31
	v_cvt_pk_bf16_f32 v4, v4, v5
	v_cvt_pk_bf16_f32 v5, v6, v7
	v_cvt_pk_bf16_f32 v6, v0, v1
	v_lshl_add_u64 v[0:1], s[40:41], 1, v[12:13]
	v_cvt_pk_bf16_f32 v7, v2, v3
	v_lshl_add_u64 v[0:1], v[122:123], 1, v[0:1]
	v_mov_b32_e32 v14, v26
	global_store_dwordx4 v[0:1], v[4:7], off offset:256 sc1
	s_and_b64 vcc, exec, s[48:49]
	s_cbranch_vccnz .LBB0_465
